# write-through (sc1) stores of the FFN hidden activations in P1 and P8, on top of earlier neutral edits
# speedup vs baseline: 1.0104x; 1.0063x over previous
.LBB0_283:
	v_mul_f32_e32 v147, 0xbfb8aa3b, v124
	v_exp_f32_e32 v147, v147
	v_mul_f32_e32 v154, 0xbfb8aa3b, v125
	v_exp_f32_e32 v154, v154
	s_lshl_b32 s19, s62, 8
	v_add_f32_e32 v147, 1.0, v147
	v_rcp_f32_e32 v147, v147
	v_add_f32_e32 v154, 1.0, v154
	v_rcp_f32_e32 v154, v154
	s_add_i32 s19, s19, s77
	v_mul_f32_e32 v124, v124, v147
	v_mul_f32_e32 v116, v124, v116
	v_mul_f32_e32 v124, v125, v154
	v_mul_f32_e32 v125, 0xbfb8aa3b, v126
	v_exp_f32_e32 v125, v125
	v_mul_f32_e32 v147, 0xbfb8aa3b, v127
	v_exp_f32_e32 v147, v147
	v_mul_f32_e32 v117, v124, v117
	v_add_f32_e32 v124, 1.0, v125
	v_rcp_f32_e32 v124, v124
	v_add_f32_e32 v125, 1.0, v147
	v_mul_f32_e32 v147, 0xbfb8aa3b, v120
	v_rcp_f32_e32 v125, v125
	v_exp_f32_e32 v147, v147
	v_mul_f32_e32 v124, v126, v124
	v_mul_f32_e32 v118, v124, v118
	v_mul_f32_e32 v124, v127, v125
	v_add_f32_e32 v125, 1.0, v147
	v_rcp_f32_e32 v125, v125
	v_mul_f32_e32 v126, 0xbfb8aa3b, v121
	v_exp_f32_e32 v126, v126
	v_mul_f32_e32 v119, v124, v119
	v_mul_f32_e32 v120, v120, v125
	v_mul_f32_e32 v120, v120, v112
	v_add_f32_e32 v112, 1.0, v126
	v_mul_f32_e32 v124, 0xbfb8aa3b, v122
	v_rcp_f32_e32 v112, v112
	v_exp_f32_e32 v124, v124
	v_mul_f32_e32 v125, 0xbfb8aa3b, v123
	v_exp_f32_e32 v125, v125
	v_mul_f32_e32 v112, v121, v112
	v_add_f32_e32 v121, 1.0, v124
	v_rcp_f32_e32 v121, v121
	v_add_f32_e32 v124, 1.0, v125
	v_rcp_f32_e32 v124, v124
	v_mul_f32_e32 v125, v112, v113
	v_mul_f32_e32 v112, v122, v121
	v_mul_f32_e32 v121, v112, v114
	v_mul_f32_e32 v112, v123, v124
	v_mul_f32_e32 v115, v112, v115
	v_cvt_pk_bf16_f32 v112, v116, v117
	v_cvt_pk_bf16_f32 v113, v118, v119
	v_mul_f32_e32 v118, 0xbfb8aa3b, v108
	v_exp_f32_e32 v118, v118
	v_mul_f32_e32 v119, 0xbfb8aa3b, v109
	s_lshl_b32 s18, s18, 7
	v_exp_f32_e32 v119, v119
	v_or_b32_e32 v136, s19, v148
	s_or_b32 s18, s18, s78
	s_ashr_i32 s19, s19, 8
	s_ashr_i32 s18, s18, 6
	s_mul_i32 s19, s19, 44
	s_add_i32 s34, s19, s18
	v_add_f32_e32 v118, 1.0, v118
	s_ashr_i32 s35, s34, 31
	v_rcp_f32_e32 v118, v118
	v_add_f32_e32 v119, 1.0, v119
	s_lshl_b64 s[34:35], s[34:35], 15
	v_rcp_f32_e32 v119, v119
	s_add_u32 s34, s46, s34
	v_lshlrev_b32_e32 v116, 7, v136
	v_add_u32_e32 v153, 0x80, v136
	s_addc_u32 s35, s47, s35
	v_and_b32_e32 v136, 0x6780, v116
	v_lshl_add_u64 v[116:117], s[34:35], 0, v[136:137]
	v_mov_b32_e32 v147, v137
	v_mul_f32_e32 v108, v108, v118
	v_lshl_add_u64 v[116:117], v[116:117], 0, v[146:147]
	v_mul_f32_e32 v100, v108, v100
	v_mul_f32_e32 v108, v109, v119
	v_mul_f32_e32 v109, 0xbfb8aa3b, v110
	v_cvt_pk_bf16_f32 v114, v120, v125
	v_cvt_pk_bf16_f32 v115, v121, v115
	global_store_dwordx4 v[116:117], v[112:115], off sc1
	v_exp_f32_e32 v109, v109
	v_mul_f32_e32 v101, v108, v101
	v_mul_f32_e32 v112, 0xbfb8aa3b, v111
	v_exp_f32_e32 v112, v112
	v_add_f32_e32 v108, 1.0, v109
	v_rcp_f32_e32 v108, v108
	v_add_f32_e32 v109, 1.0, v112
	v_mul_f32_e32 v112, 0xbfb8aa3b, v104
	v_rcp_f32_e32 v109, v109
	v_exp_f32_e32 v112, v112
	v_mul_f32_e32 v108, v110, v108
	v_mul_f32_e32 v102, v108, v102
	v_mul_f32_e32 v108, v111, v109
	v_add_f32_e32 v109, 1.0, v112
	v_rcp_f32_e32 v109, v109
	v_mul_f32_e32 v110, 0xbfb8aa3b, v105
	v_exp_f32_e32 v110, v110
	v_mul_f32_e32 v103, v108, v103
	v_mul_f32_e32 v104, v104, v109
	v_mul_f32_e32 v104, v104, v96
	v_add_f32_e32 v96, 1.0, v110
	v_mul_f32_e32 v108, 0xbfb8aa3b, v106
	v_rcp_f32_e32 v96, v96
	v_exp_f32_e32 v108, v108
	v_mul_f32_e32 v109, 0xbfb8aa3b, v107
	v_exp_f32_e32 v109, v109
	v_mul_f32_e32 v96, v105, v96
	v_add_f32_e32 v105, 1.0, v108
	v_rcp_f32_e32 v105, v105
	v_add_f32_e32 v108, 1.0, v109
	v_rcp_f32_e32 v108, v108
	v_mul_f32_e32 v109, v96, v97
	v_mul_f32_e32 v96, v106, v105
	v_mul_f32_e32 v105, v96, v98
	v_mul_f32_e32 v96, v107, v108
	v_mul_f32_e32 v99, v96, v99
	v_cvt_pk_bf16_f32 v96, v100, v101
	v_mul_f32_e32 v100, 0xbfb8aa3b, v92
	v_exp_f32_e32 v100, v100
	v_mul_f32_e32 v101, 0xbfb8aa3b, v93
	v_exp_f32_e32 v101, v101
	v_cvt_pk_bf16_f32 v97, v102, v103
	v_add_f32_e32 v100, 1.0, v100
	v_rcp_f32_e32 v100, v100
	v_add_f32_e32 v101, 1.0, v101
	v_rcp_f32_e32 v101, v101
	v_cvt_pk_bf16_f32 v98, v104, v109
	v_mul_f32_e32 v92, v92, v100
	v_mul_f32_e32 v84, v92, v84
	v_mul_f32_e32 v92, v93, v101
	v_mul_f32_e32 v93, 0xbfb8aa3b, v94
	v_cvt_pk_bf16_f32 v99, v105, v99
	global_store_dwordx4 v[116:117], v[96:99], off offset:2048 sc1
	v_exp_f32_e32 v93, v93
	v_mul_f32_e32 v85, v92, v85
	v_mul_f32_e32 v96, 0xbfb8aa3b, v95
	v_exp_f32_e32 v96, v96
	v_add_f32_e32 v92, 1.0, v93
	v_rcp_f32_e32 v92, v92
	v_add_f32_e32 v93, 1.0, v96
	v_mul_f32_e32 v96, 0xbfb8aa3b, v88
	v_rcp_f32_e32 v93, v93
	v_exp_f32_e32 v96, v96
	v_mul_f32_e32 v92, v94, v92
	v_mul_f32_e32 v86, v92, v86
	v_mul_f32_e32 v92, v95, v93
	v_add_f32_e32 v93, 1.0, v96
	v_rcp_f32_e32 v93, v93
	v_mul_f32_e32 v94, 0xbfb8aa3b, v89
	v_exp_f32_e32 v94, v94
	v_mul_f32_e32 v87, v92, v87
	v_mul_f32_e32 v88, v88, v93
	v_mul_f32_e32 v88, v88, v80
	v_add_f32_e32 v80, 1.0, v94
	v_mul_f32_e32 v92, 0xbfb8aa3b, v90
	v_rcp_f32_e32 v80, v80
	v_exp_f32_e32 v92, v92
	v_mul_f32_e32 v93, 0xbfb8aa3b, v91
	v_exp_f32_e32 v93, v93
	v_mul_f32_e32 v80, v89, v80
	v_add_f32_e32 v89, 1.0, v92
	v_rcp_f32_e32 v89, v89
	v_add_f32_e32 v92, 1.0, v93
	v_rcp_f32_e32 v92, v92
	v_mul_f32_e32 v93, v80, v81
	v_mul_f32_e32 v80, v90, v89
	v_mul_f32_e32 v89, v80, v82
	v_mul_f32_e32 v80, v91, v92
	v_mul_f32_e32 v83, v80, v83
	v_cvt_pk_bf16_f32 v80, v84, v85
	v_mul_f32_e32 v84, 0xbfb8aa3b, v76
	v_cvt_pk_bf16_f32 v81, v86, v87
	v_exp_f32_e32 v86, v84
	v_mul_f32_e32 v84, 0xbfb8aa3b, v77
	v_exp_f32_e32 v87, v84
	v_add_co_u32_e32 v84, vcc, s85, v116
	v_add_f32_e32 v86, 1.0, v86
	v_rcp_f32_e32 v86, v86
	v_add_f32_e32 v87, 1.0, v87
	v_rcp_f32_e32 v87, v87
	v_addc_co_u32_e32 v85, vcc, 0, v117, vcc
	v_mul_f32_e32 v76, v76, v86
	v_mul_f32_e32 v68, v76, v68
	v_mul_f32_e32 v76, v77, v87
	v_mul_f32_e32 v77, 0xbfb8aa3b, v78
	v_cvt_pk_bf16_f32 v82, v88, v93
	v_cvt_pk_bf16_f32 v83, v89, v83
	global_store_dwordx4 v[84:85], v[80:83], off sc1
	v_exp_f32_e32 v77, v77
	v_mul_f32_e32 v69, v76, v69
	v_mul_f32_e32 v80, 0xbfb8aa3b, v79
	v_exp_f32_e32 v80, v80
	v_add_f32_e32 v76, 1.0, v77
	v_rcp_f32_e32 v76, v76
	v_add_f32_e32 v77, 1.0, v80
	v_mul_f32_e32 v80, 0xbfb8aa3b, v72
	v_rcp_f32_e32 v77, v77
	v_exp_f32_e32 v80, v80
	v_mul_f32_e32 v76, v78, v76
	v_mul_f32_e32 v70, v76, v70
	v_mul_f32_e32 v76, v79, v77
	v_add_f32_e32 v77, 1.0, v80
	v_rcp_f32_e32 v77, v77
	v_mul_f32_e32 v78, 0xbfb8aa3b, v73
	v_exp_f32_e32 v78, v78
	v_mul_f32_e32 v71, v76, v71
	v_mul_f32_e32 v72, v72, v77
	v_mul_f32_e32 v72, v72, v64
	v_add_f32_e32 v64, 1.0, v78
	v_mul_f32_e32 v76, 0xbfb8aa3b, v74
	v_rcp_f32_e32 v64, v64
	v_exp_f32_e32 v76, v76
	v_mul_f32_e32 v77, 0xbfb8aa3b, v75
	v_exp_f32_e32 v77, v77
	v_mul_f32_e32 v64, v73, v64
	v_add_f32_e32 v73, 1.0, v76
	v_rcp_f32_e32 v73, v73
	v_add_f32_e32 v76, 1.0, v77
	v_rcp_f32_e32 v76, v76
	v_mul_f32_e32 v77, v64, v65
	v_mul_f32_e32 v64, v74, v73
	v_mul_f32_e32 v73, v64, v66
	v_mul_f32_e32 v64, v75, v76
	v_mul_f32_e32 v67, v64, v67
	v_cvt_pk_bf16_f32 v64, v68, v69
	v_cvt_pk_bf16_f32 v65, v70, v71
	v_cvt_pk_bf16_f32 v66, v72, v77
	v_cvt_pk_bf16_f32 v67, v73, v67
	global_store_dwordx4 v[84:85], v[64:67], off offset:2048 sc1
	s_nop 1
	v_mul_f32_e32 v65, 0xbfb8aa3b, v60
	v_exp_f32_e32 v66, v65
	v_mul_f32_e32 v65, 0xbfb8aa3b, v61
	v_exp_f32_e32 v67, v65
	v_lshrrev_b32_e32 v64, 8, v153
	v_add_f32_e32 v66, 1.0, v66
	v_rcp_f32_e32 v66, v66
	v_add_f32_e32 v67, 1.0, v67
	v_rcp_f32_e32 v67, v67
	v_mad_i32_i24 v64, v64, 44, s18
	v_mul_f32_e32 v60, v60, v66
	v_mul_f32_e32 v52, v60, v52
	v_mul_f32_e32 v60, v61, v67
	v_mul_f32_e32 v61, 0xbfb8aa3b, v62
	v_exp_f32_e32 v61, v61
	v_mul_f32_e32 v66, 0xbfb8aa3b, v63
	v_exp_f32_e32 v66, v66
	v_mul_f32_e32 v53, v60, v53
	v_add_f32_e32 v60, 1.0, v61
	v_rcp_f32_e32 v60, v60
	v_add_f32_e32 v61, 1.0, v66
	v_mul_f32_e32 v66, 0xbfb8aa3b, v56
	v_rcp_f32_e32 v61, v61
	v_exp_f32_e32 v66, v66
	v_mul_f32_e32 v60, v62, v60
	v_mul_f32_e32 v54, v60, v54
	v_mul_f32_e32 v60, v63, v61
	v_add_f32_e32 v61, 1.0, v66
	v_rcp_f32_e32 v61, v61
	v_mul_f32_e32 v62, 0xbfb8aa3b, v57
	v_exp_f32_e32 v62, v62
	v_mul_f32_e32 v55, v60, v55
	v_mul_f32_e32 v56, v56, v61
	v_mul_f32_e32 v56, v56, v48
	v_add_f32_e32 v48, 1.0, v62
	v_mul_f32_e32 v60, 0xbfb8aa3b, v58
	v_rcp_f32_e32 v48, v48
	v_exp_f32_e32 v60, v60
	v_mul_f32_e32 v61, 0xbfb8aa3b, v59
	v_exp_f32_e32 v61, v61
	v_mul_f32_e32 v48, v57, v48
	v_add_f32_e32 v57, 1.0, v60
	v_rcp_f32_e32 v57, v57
	v_add_f32_e32 v60, 1.0, v61
	v_rcp_f32_e32 v60, v60
	v_mul_f32_e32 v61, v48, v49
	v_mul_f32_e32 v48, v58, v57
	v_mul_f32_e32 v57, v48, v50
	v_mul_f32_e32 v48, v59, v60
	v_mul_f32_e32 v51, v48, v51
	v_cvt_pk_bf16_f32 v48, v52, v53
	v_cvt_pk_bf16_f32 v49, v54, v55
	v_lshlrev_b32_e32 v54, 7, v153
	v_and_b32_e32 v136, 0x6780, v54
	v_mul_f32_e32 v54, 0xbfb8aa3b, v44
	v_exp_f32_e32 v54, v54
	v_mul_f32_e32 v55, 0xbfb8aa3b, v45
	v_exp_f32_e32 v55, v55
	v_ashrrev_i32_e32 v65, 31, v64
	v_add_f32_e32 v54, 1.0, v54
	v_rcp_f32_e32 v54, v54
	v_add_f32_e32 v55, 1.0, v55
	v_rcp_f32_e32 v55, v55
	v_lshlrev_b64 v[64:65], 15, v[64:65]
	v_lshl_add_u64 v[52:53], s[46:47], 0, v[64:65]
	v_lshl_add_u64 v[52:53], v[52:53], 0, v[136:137]
	v_mul_f32_e32 v44, v44, v54
	v_lshl_add_u64 v[52:53], v[52:53], 0, v[146:147]
	v_mul_f32_e32 v36, v44, v36
	v_mul_f32_e32 v44, v45, v55
	v_mul_f32_e32 v45, 0xbfb8aa3b, v46
	v_cvt_pk_bf16_f32 v50, v56, v61
	v_cvt_pk_bf16_f32 v51, v57, v51
	global_store_dwordx4 v[52:53], v[48:51], off sc1
	v_exp_f32_e32 v45, v45
	v_mul_f32_e32 v37, v44, v37
	v_mul_f32_e32 v48, 0xbfb8aa3b, v47
	v_exp_f32_e32 v48, v48
	v_add_f32_e32 v44, 1.0, v45
	v_rcp_f32_e32 v44, v44
	v_add_f32_e32 v45, 1.0, v48
	v_mul_f32_e32 v48, 0xbfb8aa3b, v40
	v_rcp_f32_e32 v45, v45
	v_exp_f32_e32 v48, v48
	v_mul_f32_e32 v44, v46, v44
	v_mul_f32_e32 v38, v44, v38
	v_mul_f32_e32 v44, v47, v45
	v_add_f32_e32 v45, 1.0, v48
	v_rcp_f32_e32 v45, v45
	v_mul_f32_e32 v46, 0xbfb8aa3b, v41
	v_exp_f32_e32 v46, v46
	v_mul_f32_e32 v39, v44, v39
	v_mul_f32_e32 v40, v40, v45
	v_mul_f32_e32 v40, v40, v32
	v_add_f32_e32 v32, 1.0, v46
	v_mul_f32_e32 v44, 0xbfb8aa3b, v42
	v_rcp_f32_e32 v32, v32
	v_exp_f32_e32 v44, v44
	v_mul_f32_e32 v45, 0xbfb8aa3b, v43
	v_exp_f32_e32 v45, v45
	v_mul_f32_e32 v32, v41, v32
	v_add_f32_e32 v41, 1.0, v44
	v_rcp_f32_e32 v41, v41
	v_add_f32_e32 v44, 1.0, v45
	v_rcp_f32_e32 v44, v44
	v_mul_f32_e32 v45, v32, v33
	v_mul_f32_e32 v32, v42, v41
	v_mul_f32_e32 v41, v32, v34
	v_mul_f32_e32 v32, v43, v44
	v_mul_f32_e32 v35, v32, v35
	v_cvt_pk_bf16_f32 v32, v36, v37
	v_mul_f32_e32 v36, 0xbfb8aa3b, v28
	v_exp_f32_e32 v36, v36
	v_mul_f32_e32 v37, 0xbfb8aa3b, v29
	v_exp_f32_e32 v37, v37
	v_cvt_pk_bf16_f32 v33, v38, v39
	v_add_f32_e32 v36, 1.0, v36
	v_rcp_f32_e32 v36, v36
	v_add_f32_e32 v37, 1.0, v37
	v_rcp_f32_e32 v37, v37
	v_cvt_pk_bf16_f32 v34, v40, v45
	v_mul_f32_e32 v28, v28, v36
	v_mul_f32_e32 v20, v28, v20
	v_mul_f32_e32 v28, v29, v37
	v_mul_f32_e32 v29, 0xbfb8aa3b, v30
	v_cvt_pk_bf16_f32 v35, v41, v35
	global_store_dwordx4 v[52:53], v[32:35], off offset:2048 sc1
	v_exp_f32_e32 v29, v29
	v_mul_f32_e32 v21, v28, v21
	v_mul_f32_e32 v32, 0xbfb8aa3b, v31
	v_exp_f32_e32 v32, v32
	v_add_f32_e32 v28, 1.0, v29
	v_rcp_f32_e32 v28, v28
	v_add_f32_e32 v29, 1.0, v32
	v_mul_f32_e32 v32, 0xbfb8aa3b, v24
	v_rcp_f32_e32 v29, v29
	v_exp_f32_e32 v32, v32
	v_mul_f32_e32 v28, v30, v28
	v_mul_f32_e32 v22, v28, v22
	v_mul_f32_e32 v28, v31, v29
	v_add_f32_e32 v29, 1.0, v32
	v_rcp_f32_e32 v29, v29
	v_mul_f32_e32 v30, 0xbfb8aa3b, v25
	v_exp_f32_e32 v30, v30
	v_mul_f32_e32 v23, v28, v23
	v_mul_f32_e32 v24, v24, v29
	v_mul_f32_e32 v24, v24, v16
	v_add_f32_e32 v16, 1.0, v30
	v_mul_f32_e32 v28, 0xbfb8aa3b, v26
	v_rcp_f32_e32 v16, v16
	v_exp_f32_e32 v28, v28
	v_mul_f32_e32 v29, 0xbfb8aa3b, v27
	v_exp_f32_e32 v29, v29
	v_mul_f32_e32 v16, v25, v16
	v_add_f32_e32 v25, 1.0, v28
	v_rcp_f32_e32 v25, v25
	v_add_f32_e32 v28, 1.0, v29
	v_rcp_f32_e32 v28, v28
	v_mul_f32_e32 v29, v16, v17
	v_mul_f32_e32 v16, v26, v25
	v_mul_f32_e32 v25, v16, v18
	v_mul_f32_e32 v16, v27, v28
	v_mul_f32_e32 v19, v16, v19
	v_cvt_pk_bf16_f32 v16, v20, v21
	v_mul_f32_e32 v20, 0xbfb8aa3b, v12
	v_cvt_pk_bf16_f32 v17, v22, v23
	v_exp_f32_e32 v22, v20
	v_mul_f32_e32 v20, 0xbfb8aa3b, v13
	v_exp_f32_e32 v23, v20
	v_add_co_u32_e32 v20, vcc, s85, v52
	v_add_f32_e32 v22, 1.0, v22
	v_rcp_f32_e32 v22, v22
	v_add_f32_e32 v23, 1.0, v23
	v_rcp_f32_e32 v23, v23
	v_addc_co_u32_e32 v21, vcc, 0, v53, vcc
	v_mul_f32_e32 v12, v12, v22
	v_mul_f32_e32 v4, v12, v4
	v_mul_f32_e32 v12, v13, v23
	v_mul_f32_e32 v13, 0xbfb8aa3b, v14
	v_cvt_pk_bf16_f32 v18, v24, v29
	v_cvt_pk_bf16_f32 v19, v25, v19
	global_store_dwordx4 v[20:21], v[16:19], off sc1
	v_exp_f32_e32 v13, v13
	v_mul_f32_e32 v5, v12, v5
	v_mul_f32_e32 v16, 0xbfb8aa3b, v15
	v_exp_f32_e32 v16, v16
	v_add_f32_e32 v12, 1.0, v13
	v_rcp_f32_e32 v12, v12
	s_andn2_b64 vcc, exec, s[0:1]
	v_add_f32_e32 v13, 1.0, v16
	v_mul_f32_e32 v16, 0xbfb8aa3b, v8
	v_rcp_f32_e32 v13, v13
	v_exp_f32_e32 v16, v16
	v_mul_f32_e32 v12, v14, v12
	v_mul_f32_e32 v6, v12, v6
	v_mul_f32_e32 v12, v15, v13
	v_add_f32_e32 v13, 1.0, v16
	v_rcp_f32_e32 v13, v13
	v_mul_f32_e32 v14, 0xbfb8aa3b, v9
	v_exp_f32_e32 v14, v14
	v_mul_f32_e32 v7, v12, v7
	v_mul_f32_e32 v8, v8, v13
	v_mul_f32_e32 v8, v8, v0
	v_add_f32_e32 v0, 1.0, v14
	v_mul_f32_e32 v12, 0xbfb8aa3b, v10
	v_rcp_f32_e32 v0, v0
	v_exp_f32_e32 v12, v12
	v_mul_f32_e32 v13, 0xbfb8aa3b, v11
	v_exp_f32_e32 v13, v13
	v_mul_f32_e32 v0, v9, v0
	v_add_f32_e32 v9, 1.0, v12
	v_rcp_f32_e32 v9, v9
	v_add_f32_e32 v12, 1.0, v13
	v_rcp_f32_e32 v12, v12
	v_mul_f32_e32 v13, v0, v1
	v_mul_f32_e32 v0, v10, v9
	v_mul_f32_e32 v9, v0, v2
	v_mul_f32_e32 v0, v11, v12
	v_mul_f32_e32 v3, v0, v3
	s_mov_b64 s[0:1], -1
	v_cvt_pk_bf16_f32 v0, v4, v5
	v_cvt_pk_bf16_f32 v1, v6, v7
	v_cvt_pk_bf16_f32 v2, v8, v13
	v_cvt_pk_bf16_f32 v3, v9, v3
	global_store_dwordx4 v[20:21], v[0:3], off offset:2048 sc1
	s_cbranch_vccnz .LBB0_276
	s_andn2_b64 vcc, exec, s[4:5]
	s_cbranch_vccnz .LBB0_275
	s_barrier
	s_branch .LBB0_275

.LBB0_1340:
	s_lshl_b32 s13, s38, 8
	s_add_i32 s15, s13, s53
	v_or_b32_e32 v154, s15, v148
	v_ashrrev_i32_e32 v155, 31, v154
	v_lshl_add_u64 v[156:157], v[154:155], 2, s[0:1]
	global_load_dword v136, v[156:157], off
	global_load_dword v147, v[156:157], off offset:64
	global_load_dword v155, v[156:157], off offset:128
	global_load_dword v160, v[156:157], off offset:192
	global_load_dword v161, v[156:157], off offset:512
	global_load_dword v162, v[156:157], off offset:576
	global_load_dword v163, v[156:157], off offset:640
	global_load_dword v164, v[156:157], off offset:704
	v_mov_b32_e32 v156, v124
	v_mov_b32_e32 v124, v126
	v_mov_b32_e32 v126, v120
	v_mov_b32_e32 v157, v116
	v_mov_b32_e32 v116, v125
	v_mov_b32_e32 v125, v118
	v_mov_b32_e32 v118, v127
	v_mov_b32_e32 v127, v112
	v_mov_b32_e32 v112, v121
	v_mov_b32_e32 v158, v122
	v_mov_b32_e32 v159, v114
	v_mov_b32_e32 v114, v123
	s_lshl_b32 s13, s18, 7
	s_or_b32 s13, s13, s54
	s_ashr_i32 s15, s15, 8
	s_ashr_i32 s13, s13, 6
	s_mul_i32 s15, s15, 44
	s_add_i32 s18, s15, s13
	s_ashr_i32 s19, s18, 31
	s_lshl_b64 s[18:19], s[18:19], 15
	s_add_u32 s18, s46, s18
	s_addc_u32 s19, s47, s19
	v_add_u32_e32 v122, 0x80, v154
	s_waitcnt vmcnt(0)
	v_fmamk_f32 v120, v136, 0x3a800000, v153
	v_rsq_f32_e32 v136, v120
	v_fmamk_f32 v147, v147, 0x3a800000, v153
	v_fmamk_f32 v155, v155, 0x3a800000, v153
	v_fmamk_f32 v160, v160, 0x3a800000, v153
	v_pk_mul_f32 v[118:119], v[118:119], v[136:137] op_sel_hi:[1,0]
	v_pk_mul_f32 v[156:157], v[156:157], v[136:137] op_sel_hi:[1,0]
	v_fmamk_f32 v120, v164, 0x3a800000, v153
	v_pk_mul_f32 v[116:117], v[116:117], v[136:137] op_sel_hi:[1,0]
	v_pk_mul_f32 v[124:125], v[124:125], v[136:137] op_sel_hi:[1,0]
	v_pk_mul_f32 v[112:113], v[112:113], v[136:137] op_sel_hi:[1,0]
	v_mul_f32_e32 v164, 0xbfb8aa3b, v119
	v_fmamk_f32 v123, v162, 0x3a800000, v153
	v_fmamk_f32 v121, v163, 0x3a800000, v153
	v_pk_mul_f32 v[126:127], v[126:127], v[136:137] op_sel_hi:[1,0]
	v_pk_mul_f32 v[158:159], v[158:159], v[136:137] op_sel_hi:[1,0]
	v_pk_mul_f32 v[114:115], v[114:115], v[136:137] op_sel_hi:[1,0]
	v_mul_f32_e32 v136, 0xbfb8aa3b, v157
	v_mul_f32_e32 v162, 0xbfb8aa3b, v117
	v_mul_f32_e32 v163, 0xbfb8aa3b, v125
	v_mul_f32_e32 v166, 0xbfb8aa3b, v113
	v_exp_f32_e32 v164, v164
	v_exp_f32_e32 v136, v136
	v_exp_f32_e32 v162, v162
	v_exp_f32_e32 v163, v163
	v_exp_f32_e32 v166, v166
	v_mul_f32_e32 v167, 0xbfb8aa3b, v159
	v_mul_f32_e32 v168, 0xbfb8aa3b, v115
	v_mul_f32_e32 v165, 0xbfb8aa3b, v127
	v_exp_f32_e32 v167, v167
	v_exp_f32_e32 v168, v168
	v_exp_f32_e32 v165, v165
	v_add_f32_e32 v164, 1.0, v164
	v_add_f32_e32 v136, 1.0, v136
	v_add_f32_e32 v162, 1.0, v162
	v_add_f32_e32 v163, 1.0, v163
	v_add_f32_e32 v166, 1.0, v166
	v_rcp_f32_e32 v164, v164
	v_rcp_f32_e32 v136, v136
	v_rcp_f32_e32 v162, v162
	v_rcp_f32_e32 v163, v163
	v_rcp_f32_e32 v166, v166
	v_add_f32_e32 v167, 1.0, v167
	v_add_f32_e32 v168, 1.0, v168
	v_add_f32_e32 v165, 1.0, v165
	v_rcp_f32_e32 v167, v167
	v_rcp_f32_e32 v168, v168
	v_rcp_f32_e32 v165, v165
	v_mul_f32_e32 v119, v119, v164
	v_mul_f32_e32 v136, v157, v136
	v_mul_f32_e32 v117, v117, v162
	v_mul_f32_e32 v125, v125, v163
	v_mul_f32_e32 v113, v113, v166
	v_mul_f32_e32 v118, v118, v119
	v_mul_f32_e32 v136, v156, v136
	v_mul_f32_e32 v116, v116, v117
	v_mul_f32_e32 v117, v124, v125
	v_mul_f32_e32 v124, v112, v113
	v_cvt_pk_bf16_f32 v112, v136, v116
	v_cvt_pk_bf16_f32 v113, v117, v118
	v_rsq_f32_e32 v118, v147
	v_mul_f32_e32 v157, v159, v167
	v_mul_f32_e32 v115, v115, v168
	v_mul_f32_e32 v127, v127, v165
	v_mul_f32_e32 v125, v158, v157
	v_mul_f32_e32 v115, v114, v115
	v_mul_f32_e32 v119, v126, v127
	v_cvt_pk_bf16_f32 v114, v119, v124
	v_cvt_pk_bf16_f32 v115, v125, v115
	v_mov_b32_e32 v124, v104
	v_mov_b32_e32 v125, v108
	v_pk_mul_f32 v[124:125], v[124:125], v[118:119] op_sel_hi:[1,0]
	v_lshlrev_b32_e32 v116, 7, v154
	v_mul_f32_e32 v104, 0xbfb8aa3b, v125
	v_exp_f32_e32 v119, v104
	v_mov_b32_e32 v108, v105
	v_and_b32_e32 v136, 0x6780, v116
	v_lshl_add_u64 v[116:117], s[18:19], 0, v[136:137]
	v_pk_mul_f32 v[104:105], v[108:109], v[118:119] op_sel_hi:[1,0]
	v_mov_b32_e32 v147, v137
	v_mul_f32_e32 v108, 0xbfb8aa3b, v105
	v_exp_f32_e32 v126, v108
	v_lshl_add_u64 v[108:109], v[116:117], 0, v[146:147]
	v_add_f32_e32 v116, 1.0, v119
	v_rcp_f32_e32 v116, v116
	global_store_dwordx4 v[108:109], v[112:115], off sc1
	v_add_f32_e32 v117, 1.0, v126
	v_rcp_f32_e32 v117, v117
	v_mul_f32_e32 v112, v125, v116
	v_mul_f32_e32 v114, v124, v112
	v_mov_b32_e32 v112, v106
	v_mov_b32_e32 v113, v110
	v_pk_mul_f32 v[112:113], v[112:113], v[118:119] op_sel_hi:[1,0]
	v_mov_b32_e32 v110, v107
	v_mul_f32_e32 v106, 0xbfb8aa3b, v113
	v_exp_f32_e32 v115, v106
	v_pk_mul_f32 v[106:107], v[110:111], v[118:119] op_sel_hi:[1,0]
	v_mul_f32_e32 v105, v105, v117
	v_mul_f32_e32 v110, 0xbfb8aa3b, v107
	v_exp_f32_e32 v110, v110
	v_mul_f32_e32 v111, v104, v105
	v_add_f32_e32 v104, 1.0, v115
	v_rcp_f32_e32 v115, v104
	v_add_f32_e32 v104, 1.0, v110
	v_rcp_f32_e32 v110, v104
	v_mov_b32_e32 v104, v96
	v_mov_b32_e32 v105, v100
	v_pk_mul_f32 v[104:105], v[104:105], v[118:119] op_sel_hi:[1,0]
	v_mul_f32_e32 v100, v113, v115
	v_mul_f32_e32 v96, 0xbfb8aa3b, v105
	v_exp_f32_e32 v96, v96
	v_mul_f32_e32 v112, v112, v100
	v_mov_b32_e32 v100, v97
	v_mul_f32_e32 v107, v107, v110
	v_add_f32_e32 v96, 1.0, v96
	v_rcp_f32_e32 v110, v96
	v_pk_mul_f32 v[96:97], v[100:101], v[118:119] op_sel_hi:[1,0]
	v_mul_f32_e32 v106, v106, v107
	v_mul_f32_e32 v100, 0xbfb8aa3b, v97
	v_exp_f32_e32 v100, v100
	v_mul_f32_e32 v101, v105, v110
	v_mul_f32_e32 v104, v104, v101
	v_mov_b32_e32 v101, v102
	v_add_f32_e32 v100, 1.0, v100
	v_rcp_f32_e32 v105, v100
	v_mov_b32_e32 v100, v98
	v_pk_mul_f32 v[100:101], v[100:101], v[118:119] op_sel_hi:[1,0]
	v_mov_b32_e32 v102, v99
	v_mul_f32_e32 v98, 0xbfb8aa3b, v101
	v_exp_f32_e32 v107, v98
	v_pk_mul_f32 v[98:99], v[102:103], v[118:119] op_sel_hi:[1,0]
	v_mul_f32_e32 v97, v97, v105
	v_mul_f32_e32 v102, 0xbfb8aa3b, v99
	v_exp_f32_e32 v102, v102
	v_add_f32_e32 v103, 1.0, v107
	v_rcp_f32_e32 v103, v103
	v_mul_f32_e32 v105, v96, v97
	v_add_f32_e32 v102, 1.0, v102
	v_rcp_f32_e32 v102, v102
	v_mul_f32_e32 v96, v101, v103
	v_mul_f32_e32 v101, v100, v96
	v_rsq_f32_e32 v100, v155
	v_mul_f32_e32 v96, v99, v102
	v_mov_b32_e32 v102, v88
	v_mov_b32_e32 v103, v92
	v_pk_mul_f32 v[102:103], v[102:103], v[100:101] op_sel_hi:[1,0]
	v_mov_b32_e32 v92, v89
	v_mul_f32_e32 v88, 0xbfb8aa3b, v103
	v_mul_f32_e32 v99, v98, v96
	v_cvt_pk_bf16_f32 v96, v114, v111
	v_cvt_pk_bf16_f32 v97, v112, v106
	v_cvt_pk_bf16_f32 v98, v104, v105
	v_exp_f32_e32 v104, v88
	v_pk_mul_f32 v[88:89], v[92:93], v[100:101] op_sel_hi:[1,0]
	v_cvt_pk_bf16_f32 v99, v101, v99
	global_store_dwordx4 v[108:109], v[96:99], off offset:2048 sc1
	v_mul_f32_e32 v92, 0xbfb8aa3b, v89
	v_exp_f32_e32 v92, v92
	v_add_f32_e32 v93, 1.0, v104
	v_rcp_f32_e32 v93, v93
	v_fmamk_f32 v161, v161, 0x3a800000, v153
	v_add_f32_e32 v92, 1.0, v92
	v_rcp_f32_e32 v92, v92
	v_mul_f32_e32 v93, v103, v93
	v_mul_f32_e32 v96, v102, v93
	v_mov_b32_e32 v93, v94
	v_mul_f32_e32 v89, v89, v92
	v_mov_b32_e32 v92, v90
	v_pk_mul_f32 v[92:93], v[92:93], v[100:101] op_sel_hi:[1,0]
	v_mov_b32_e32 v94, v91
	v_mul_f32_e32 v90, 0xbfb8aa3b, v93
	v_exp_f32_e32 v97, v90
	v_pk_mul_f32 v[90:91], v[94:95], v[100:101] op_sel_hi:[1,0]
	v_mul_f32_e32 v95, v88, v89
	v_mul_f32_e32 v94, 0xbfb8aa3b, v91
	v_exp_f32_e32 v94, v94
	v_add_f32_e32 v88, 1.0, v97
	v_rcp_f32_e32 v97, v88
	v_mov_b32_e32 v89, v84
	v_add_f32_e32 v88, 1.0, v94
	v_rcp_f32_e32 v94, v88
	v_mov_b32_e32 v88, v80
	v_pk_mul_f32 v[88:89], v[88:89], v[100:101] op_sel_hi:[1,0]
	v_mul_f32_e32 v84, v93, v97
	v_mul_f32_e32 v80, 0xbfb8aa3b, v89
	v_exp_f32_e32 v80, v80
	v_mul_f32_e32 v92, v92, v84
	v_mov_b32_e32 v84, v81
	v_mul_f32_e32 v91, v91, v94
	v_add_f32_e32 v80, 1.0, v80
	v_rcp_f32_e32 v93, v80
	v_pk_mul_f32 v[80:81], v[84:85], v[100:101] op_sel_hi:[1,0]
	v_mul_f32_e32 v90, v90, v91
	v_mul_f32_e32 v84, 0xbfb8aa3b, v81
	v_exp_f32_e32 v84, v84
	v_mul_f32_e32 v85, v89, v93
	v_mul_f32_e32 v88, v88, v85
	v_mov_b32_e32 v85, v86
	v_add_f32_e32 v84, 1.0, v84
	v_rcp_f32_e32 v89, v84
	v_mov_b32_e32 v84, v82
	v_pk_mul_f32 v[84:85], v[84:85], v[100:101] op_sel_hi:[1,0]
	v_mov_b32_e32 v86, v83
	v_mul_f32_e32 v82, 0xbfb8aa3b, v85
	v_exp_f32_e32 v91, v82
	v_pk_mul_f32 v[82:83], v[86:87], v[100:101] op_sel_hi:[1,0]
	v_mul_f32_e32 v81, v81, v89
	v_mul_f32_e32 v86, 0xbfb8aa3b, v83
	v_exp_f32_e32 v86, v86
	v_add_f32_e32 v87, 1.0, v91
	v_rcp_f32_e32 v87, v87
	v_mul_f32_e32 v89, v80, v81
	v_add_f32_e32 v86, 1.0, v86
	v_rcp_f32_e32 v86, v86
	v_mul_f32_e32 v80, v85, v87
	v_mul_f32_e32 v85, v84, v80
	v_rsq_f32_e32 v84, v160
	v_mul_f32_e32 v80, v83, v86
	v_mov_b32_e32 v86, v72
	v_mov_b32_e32 v87, v76
	v_pk_mul_f32 v[86:87], v[86:87], v[84:85] op_sel_hi:[1,0]
	v_mul_f32_e32 v83, v82, v80
	v_mul_f32_e32 v72, 0xbfb8aa3b, v87
	v_cvt_pk_bf16_f32 v80, v96, v95
	v_cvt_pk_bf16_f32 v81, v92, v90
	v_cvt_pk_bf16_f32 v82, v88, v89
	v_cvt_pk_bf16_f32 v83, v85, v83
	v_exp_f32_e32 v85, v72
	v_mov_b32_e32 v76, v73
	v_pk_mul_f32 v[72:73], v[76:77], v[84:85] op_sel_hi:[1,0]
	v_add_f32_e32 v85, 1.0, v85
	v_rcp_f32_e32 v85, v85
	v_mul_f32_e32 v76, 0xbfb8aa3b, v73
	v_exp_f32_e32 v88, v76
	v_add_co_u32_e32 v76, vcc, s61, v108
	v_add_f32_e32 v88, 1.0, v88
	s_nop 0
	v_addc_co_u32_e32 v77, vcc, 0, v109, vcc
	global_store_dwordx4 v[76:77], v[80:83], off sc1
	v_rcp_f32_e32 v88, v88
	s_nop 0
	v_mul_f32_e32 v80, v87, v85
	v_mul_f32_e32 v82, v86, v80
	v_mov_b32_e32 v80, v74
	v_mov_b32_e32 v81, v78
	v_pk_mul_f32 v[80:81], v[80:81], v[84:85] op_sel_hi:[1,0]
	v_mov_b32_e32 v78, v75
	v_mul_f32_e32 v74, 0xbfb8aa3b, v81
	v_exp_f32_e32 v83, v74
	v_pk_mul_f32 v[74:75], v[78:79], v[84:85] op_sel_hi:[1,0]
	v_mul_f32_e32 v73, v73, v88
	v_mul_f32_e32 v78, 0xbfb8aa3b, v75
	v_exp_f32_e32 v78, v78
	v_mul_f32_e32 v79, v72, v73
	v_add_f32_e32 v72, 1.0, v83
	v_rcp_f32_e32 v83, v72
	v_add_f32_e32 v72, 1.0, v78
	v_rcp_f32_e32 v78, v72
	v_mov_b32_e32 v72, v64
	v_mov_b32_e32 v73, v68
	v_pk_mul_f32 v[72:73], v[72:73], v[84:85] op_sel_hi:[1,0]
	v_mul_f32_e32 v68, v81, v83
	v_mul_f32_e32 v64, 0xbfb8aa3b, v73
	v_exp_f32_e32 v64, v64
	v_mul_f32_e32 v80, v80, v68
	v_mov_b32_e32 v68, v65
	v_mul_f32_e32 v75, v75, v78
	v_add_f32_e32 v64, 1.0, v64
	v_rcp_f32_e32 v78, v64
	v_pk_mul_f32 v[64:65], v[68:69], v[84:85] op_sel_hi:[1,0]
	v_mul_f32_e32 v74, v74, v75
	v_mul_f32_e32 v68, 0xbfb8aa3b, v65
	v_exp_f32_e32 v68, v68
	v_mul_f32_e32 v69, v73, v78
	v_mul_f32_e32 v72, v72, v69
	v_mov_b32_e32 v69, v70
	v_add_f32_e32 v68, 1.0, v68
	v_rcp_f32_e32 v73, v68
	v_mov_b32_e32 v68, v66
	v_pk_mul_f32 v[68:69], v[68:69], v[84:85] op_sel_hi:[1,0]
	v_mov_b32_e32 v70, v67
	v_mul_f32_e32 v66, 0xbfb8aa3b, v69
	v_exp_f32_e32 v75, v66
	v_pk_mul_f32 v[66:67], v[70:71], v[84:85] op_sel_hi:[1,0]
	v_mul_f32_e32 v65, v65, v73
	v_mul_f32_e32 v70, 0xbfb8aa3b, v67
	v_exp_f32_e32 v70, v70
	v_add_f32_e32 v71, 1.0, v75
	v_rcp_f32_e32 v71, v71
	v_mul_f32_e32 v73, v64, v65
	v_add_f32_e32 v70, 1.0, v70
	v_rcp_f32_e32 v70, v70
	v_mul_f32_e32 v64, v69, v71
	v_mul_f32_e32 v68, v68, v64
	v_mov_b32_e32 v69, v60
	v_mul_f32_e32 v64, v67, v70
	v_mul_f32_e32 v67, v66, v64
	v_cvt_pk_bf16_f32 v64, v82, v79
	v_cvt_pk_bf16_f32 v65, v80, v74
	v_cvt_pk_bf16_f32 v66, v72, v73
	v_cvt_pk_bf16_f32 v67, v68, v67
	global_store_dwordx4 v[76:77], v[64:67], off offset:2048 sc1
	v_mov_b32_e32 v68, v56
	v_mov_b32_e32 v60, v57
	v_rsq_f32_e32 v64, v161
	v_lshrrev_b32_e32 v65, 8, v122
	v_mad_i32_i24 v66, v65, 44, s13
	v_ashrrev_i32_e32 v67, 31, v66
	v_pk_mul_f32 v[68:69], v[68:69], v[64:65] op_sel_hi:[1,0]
	s_nop 0
	v_mul_f32_e32 v56, 0xbfb8aa3b, v69
	v_exp_f32_e32 v65, v56
	s_nop 0
	v_pk_mul_f32 v[56:57], v[60:61], v[64:65] op_sel_hi:[1,0]
	s_nop 0
	v_mul_f32_e32 v60, 0xbfb8aa3b, v57
	v_add_f32_e32 v61, 1.0, v65
	v_exp_f32_e32 v60, v60
	v_rcp_f32_e32 v65, v61
	v_add_f32_e32 v60, 1.0, v60
	v_mul_f32_e32 v65, v69, v65
	v_rcp_f32_e32 v70, v60
	v_lshlrev_b64 v[60:61], 15, v[66:67]
	v_mul_f32_e32 v65, v68, v65
	v_mov_b32_e32 v66, v58
	v_mov_b32_e32 v67, v62
	v_pk_mul_f32 v[66:67], v[66:67], v[64:65] op_sel_hi:[1,0]
	v_mov_b32_e32 v62, v59
	v_mul_f32_e32 v58, 0xbfb8aa3b, v67
	v_exp_f32_e32 v68, v58
	v_pk_mul_f32 v[58:59], v[62:63], v[64:65] op_sel_hi:[1,0]
	v_mul_f32_e32 v57, v57, v70
	v_mul_f32_e32 v62, 0xbfb8aa3b, v59
	v_exp_f32_e32 v62, v62
	v_mul_f32_e32 v63, v56, v57
	v_add_f32_e32 v56, 1.0, v68
	v_rcp_f32_e32 v68, v56
	v_add_f32_e32 v56, 1.0, v62
	v_rcp_f32_e32 v62, v56
	v_mov_b32_e32 v56, v48
	v_mov_b32_e32 v57, v52
	v_pk_mul_f32 v[56:57], v[56:57], v[64:65] op_sel_hi:[1,0]
	v_mul_f32_e32 v52, v67, v68
	v_mul_f32_e32 v48, 0xbfb8aa3b, v57
	v_exp_f32_e32 v48, v48
	v_mul_f32_e32 v66, v66, v52
	v_mov_b32_e32 v52, v49
	v_mul_f32_e32 v59, v59, v62
	v_add_f32_e32 v48, 1.0, v48
	v_rcp_f32_e32 v62, v48
	v_pk_mul_f32 v[48:49], v[52:53], v[64:65] op_sel_hi:[1,0]
	v_mul_f32_e32 v58, v58, v59
	v_mul_f32_e32 v52, 0xbfb8aa3b, v49
	v_exp_f32_e32 v52, v52
	v_mul_f32_e32 v53, v57, v62
	v_mul_f32_e32 v56, v56, v53
	v_mov_b32_e32 v53, v54
	v_add_f32_e32 v52, 1.0, v52
	v_rcp_f32_e32 v57, v52
	v_mov_b32_e32 v52, v50
	v_pk_mul_f32 v[52:53], v[52:53], v[64:65] op_sel_hi:[1,0]
	v_mov_b32_e32 v54, v51
	v_mul_f32_e32 v50, 0xbfb8aa3b, v53
	v_exp_f32_e32 v59, v50
	v_pk_mul_f32 v[50:51], v[54:55], v[64:65] op_sel_hi:[1,0]
	v_mul_f32_e32 v49, v49, v57
	v_mul_f32_e32 v54, 0xbfb8aa3b, v51
	v_exp_f32_e32 v54, v54
	v_add_f32_e32 v55, 1.0, v59
	v_rcp_f32_e32 v55, v55
	v_mul_f32_e32 v57, v48, v49
	v_add_f32_e32 v54, 1.0, v54
	v_rcp_f32_e32 v54, v54
	v_mul_f32_e32 v48, v53, v55
	v_mul_f32_e32 v52, v52, v48
	v_mul_f32_e32 v48, v51, v54
	v_lshlrev_b32_e32 v54, 7, v122
	v_and_b32_e32 v136, 0x6780, v54
	v_rsq_f32_e32 v54, v123
	v_mul_f32_e32 v51, v50, v48
	v_cvt_pk_bf16_f32 v48, v65, v63
	v_cvt_pk_bf16_f32 v49, v66, v58
	v_cvt_pk_bf16_f32 v50, v56, v57
	v_mov_b32_e32 v56, v40
	v_mov_b32_e32 v57, v44
	v_pk_mul_f32 v[56:57], v[56:57], v[54:55] op_sel_hi:[1,0]
	v_mov_b32_e32 v44, v41
	v_mul_f32_e32 v40, 0xbfb8aa3b, v57
	v_exp_f32_e32 v55, v40
	v_cvt_pk_bf16_f32 v51, v52, v51
	v_lshl_add_u64 v[52:53], s[46:47], 0, v[60:61]
	v_lshl_add_u64 v[52:53], v[52:53], 0, v[136:137]
	v_pk_mul_f32 v[40:41], v[44:45], v[54:55] op_sel_hi:[1,0]
	s_nop 0
	v_mul_f32_e32 v44, 0xbfb8aa3b, v41
	v_exp_f32_e32 v58, v44
	v_lshl_add_u64 v[44:45], v[52:53], 0, v[146:147]
	v_add_f32_e32 v52, 1.0, v55
	v_rcp_f32_e32 v52, v52
	global_store_dwordx4 v[44:45], v[48:51], off sc1
	v_add_f32_e32 v53, 1.0, v58
	v_rcp_f32_e32 v53, v53
	v_mul_f32_e32 v48, v57, v52
	v_mul_f32_e32 v50, v56, v48
	v_mov_b32_e32 v48, v42
	v_mov_b32_e32 v49, v46
	v_pk_mul_f32 v[48:49], v[48:49], v[54:55] op_sel_hi:[1,0]
	v_mov_b32_e32 v46, v43
	v_mul_f32_e32 v42, 0xbfb8aa3b, v49
	v_exp_f32_e32 v51, v42
	v_pk_mul_f32 v[42:43], v[46:47], v[54:55] op_sel_hi:[1,0]
	v_mul_f32_e32 v41, v41, v53
	v_mul_f32_e32 v46, 0xbfb8aa3b, v43
	v_exp_f32_e32 v46, v46
	v_mul_f32_e32 v47, v40, v41
	v_add_f32_e32 v40, 1.0, v51
	v_rcp_f32_e32 v51, v40
	v_add_f32_e32 v40, 1.0, v46
	v_rcp_f32_e32 v46, v40
	v_mov_b32_e32 v40, v32
	v_mov_b32_e32 v41, v36
	v_pk_mul_f32 v[40:41], v[40:41], v[54:55] op_sel_hi:[1,0]
	v_mul_f32_e32 v36, v49, v51
	v_mul_f32_e32 v32, 0xbfb8aa3b, v41
	v_exp_f32_e32 v32, v32
	v_mul_f32_e32 v48, v48, v36
	v_mov_b32_e32 v36, v33
	v_mul_f32_e32 v43, v43, v46
	v_add_f32_e32 v32, 1.0, v32
	v_rcp_f32_e32 v46, v32
	v_pk_mul_f32 v[32:33], v[36:37], v[54:55] op_sel_hi:[1,0]
	v_mul_f32_e32 v42, v42, v43
	v_mul_f32_e32 v36, 0xbfb8aa3b, v33
	v_exp_f32_e32 v36, v36
	v_mul_f32_e32 v37, v41, v46
	v_mul_f32_e32 v40, v40, v37
	v_mov_b32_e32 v37, v38
	v_add_f32_e32 v36, 1.0, v36
	v_rcp_f32_e32 v41, v36
	v_mov_b32_e32 v36, v34
	v_pk_mul_f32 v[36:37], v[36:37], v[54:55] op_sel_hi:[1,0]
	v_mov_b32_e32 v38, v35
	v_mul_f32_e32 v34, 0xbfb8aa3b, v37
	v_exp_f32_e32 v43, v34
	v_pk_mul_f32 v[34:35], v[38:39], v[54:55] op_sel_hi:[1,0]
	v_mul_f32_e32 v33, v33, v41
	v_mul_f32_e32 v38, 0xbfb8aa3b, v35
	v_exp_f32_e32 v38, v38
	v_add_f32_e32 v39, 1.0, v43
	v_rcp_f32_e32 v39, v39
	v_mul_f32_e32 v41, v32, v33
	v_add_f32_e32 v38, 1.0, v38
	v_rcp_f32_e32 v38, v38
	v_mul_f32_e32 v32, v37, v39
	v_mul_f32_e32 v37, v36, v32
	v_rsq_f32_e32 v36, v121
	v_mul_f32_e32 v32, v35, v38
	v_mov_b32_e32 v38, v24
	v_mov_b32_e32 v39, v28
	v_pk_mul_f32 v[38:39], v[38:39], v[36:37] op_sel_hi:[1,0]
	v_mov_b32_e32 v28, v25
	v_mul_f32_e32 v24, 0xbfb8aa3b, v39
	v_mul_f32_e32 v35, v34, v32
	v_cvt_pk_bf16_f32 v32, v50, v47
	v_cvt_pk_bf16_f32 v33, v48, v42
	v_cvt_pk_bf16_f32 v34, v40, v41
	v_exp_f32_e32 v40, v24
	v_pk_mul_f32 v[24:25], v[28:29], v[36:37] op_sel_hi:[1,0]
	v_cvt_pk_bf16_f32 v35, v37, v35
	global_store_dwordx4 v[44:45], v[32:35], off offset:2048 sc1
	v_mul_f32_e32 v28, 0xbfb8aa3b, v25
	v_exp_f32_e32 v28, v28
	v_add_f32_e32 v29, 1.0, v40
	v_rcp_f32_e32 v29, v29
	v_add_f32_e32 v28, 1.0, v28
	v_rcp_f32_e32 v28, v28
	v_mul_f32_e32 v29, v39, v29
	v_mul_f32_e32 v32, v38, v29
	v_mov_b32_e32 v29, v30
	v_mul_f32_e32 v25, v25, v28
	v_mov_b32_e32 v28, v26
	v_pk_mul_f32 v[28:29], v[28:29], v[36:37] op_sel_hi:[1,0]
	v_mov_b32_e32 v30, v27
	v_mul_f32_e32 v26, 0xbfb8aa3b, v29
	v_exp_f32_e32 v33, v26
	v_pk_mul_f32 v[26:27], v[30:31], v[36:37] op_sel_hi:[1,0]
	v_mul_f32_e32 v31, v24, v25
	v_mul_f32_e32 v30, 0xbfb8aa3b, v27
	v_exp_f32_e32 v30, v30
	v_add_f32_e32 v24, 1.0, v33
	v_rcp_f32_e32 v33, v24
	v_mov_b32_e32 v25, v20
	v_add_f32_e32 v24, 1.0, v30
	v_rcp_f32_e32 v30, v24
	v_mov_b32_e32 v24, v16
	v_pk_mul_f32 v[24:25], v[24:25], v[36:37] op_sel_hi:[1,0]
	v_mul_f32_e32 v20, v29, v33
	v_mul_f32_e32 v16, 0xbfb8aa3b, v25
	v_exp_f32_e32 v16, v16
	v_mul_f32_e32 v28, v28, v20
	v_mov_b32_e32 v20, v17
	v_mul_f32_e32 v27, v27, v30
	v_add_f32_e32 v16, 1.0, v16
	v_rcp_f32_e32 v29, v16
	v_pk_mul_f32 v[16:17], v[20:21], v[36:37] op_sel_hi:[1,0]
	v_mul_f32_e32 v26, v26, v27
	v_mul_f32_e32 v20, 0xbfb8aa3b, v17
	v_exp_f32_e32 v20, v20
	v_mul_f32_e32 v21, v25, v29
	v_mul_f32_e32 v24, v24, v21
	v_mov_b32_e32 v21, v22
	v_add_f32_e32 v20, 1.0, v20
	v_rcp_f32_e32 v25, v20
	v_mov_b32_e32 v20, v18
	v_pk_mul_f32 v[20:21], v[20:21], v[36:37] op_sel_hi:[1,0]
	v_mov_b32_e32 v22, v19
	v_mul_f32_e32 v18, 0xbfb8aa3b, v21
	v_exp_f32_e32 v27, v18
	v_pk_mul_f32 v[18:19], v[22:23], v[36:37] op_sel_hi:[1,0]
	v_mul_f32_e32 v17, v17, v25
	v_mul_f32_e32 v22, 0xbfb8aa3b, v19
	v_exp_f32_e32 v22, v22
	v_add_f32_e32 v23, 1.0, v27
	v_rcp_f32_e32 v23, v23
	v_mul_f32_e32 v25, v16, v17
	v_add_f32_e32 v22, 1.0, v22
	v_rcp_f32_e32 v22, v22
	v_mul_f32_e32 v16, v21, v23
	v_mul_f32_e32 v21, v20, v16
	v_rsq_f32_e32 v20, v120
	v_mul_f32_e32 v16, v19, v22
	v_mov_b32_e32 v22, v8
	v_mov_b32_e32 v23, v12
	v_pk_mul_f32 v[22:23], v[22:23], v[20:21] op_sel_hi:[1,0]
	v_mul_f32_e32 v19, v18, v16
	v_mul_f32_e32 v8, 0xbfb8aa3b, v23
	v_cvt_pk_bf16_f32 v16, v32, v31
	v_cvt_pk_bf16_f32 v17, v28, v26
	v_cvt_pk_bf16_f32 v18, v24, v25
	v_cvt_pk_bf16_f32 v19, v21, v19
	v_exp_f32_e32 v21, v8
	v_mov_b32_e32 v12, v9
	v_pk_mul_f32 v[8:9], v[12:13], v[20:21] op_sel_hi:[1,0]
	v_add_f32_e32 v21, 1.0, v21
	v_rcp_f32_e32 v21, v21
	v_mul_f32_e32 v12, 0xbfb8aa3b, v9
	v_exp_f32_e32 v24, v12
	v_add_co_u32_e32 v12, vcc, s61, v44
	v_add_f32_e32 v24, 1.0, v24
	s_nop 0
	v_addc_co_u32_e32 v13, vcc, 0, v45, vcc
	global_store_dwordx4 v[12:13], v[16:19], off sc1
	v_rcp_f32_e32 v24, v24
	s_andn2_b64 vcc, exec, s[4:5]
	v_mul_f32_e32 v16, v23, v21
	v_mul_f32_e32 v18, v22, v16
	v_mov_b32_e32 v16, v10
	v_mov_b32_e32 v17, v14
	v_pk_mul_f32 v[16:17], v[16:17], v[20:21] op_sel_hi:[1,0]
	v_mov_b32_e32 v14, v11
	v_mul_f32_e32 v10, 0xbfb8aa3b, v17
	v_exp_f32_e32 v19, v10
	v_pk_mul_f32 v[10:11], v[14:15], v[20:21] op_sel_hi:[1,0]
	v_mul_f32_e32 v9, v9, v24
	v_mul_f32_e32 v14, 0xbfb8aa3b, v11
	v_exp_f32_e32 v14, v14
	v_mul_f32_e32 v15, v8, v9
	v_add_f32_e32 v8, 1.0, v19
	v_rcp_f32_e32 v19, v8
	v_add_f32_e32 v8, 1.0, v14
	v_rcp_f32_e32 v14, v8
	v_mov_b32_e32 v8, v0
	v_mov_b32_e32 v9, v4
	v_pk_mul_f32 v[8:9], v[8:9], v[20:21] op_sel_hi:[1,0]
	v_mul_f32_e32 v4, v17, v19
	v_mul_f32_e32 v0, 0xbfb8aa3b, v9
	v_exp_f32_e32 v0, v0
	v_mul_f32_e32 v16, v16, v4
	v_mov_b32_e32 v4, v1
	v_mul_f32_e32 v11, v11, v14
	v_add_f32_e32 v0, 1.0, v0
	v_rcp_f32_e32 v14, v0
	v_pk_mul_f32 v[0:1], v[4:5], v[20:21] op_sel_hi:[1,0]
	v_mul_f32_e32 v10, v10, v11
	v_mul_f32_e32 v4, 0xbfb8aa3b, v1
	v_exp_f32_e32 v4, v4
	v_mul_f32_e32 v5, v9, v14
	v_mul_f32_e32 v8, v8, v5
	v_mov_b32_e32 v5, v6
	v_add_f32_e32 v4, 1.0, v4
	v_rcp_f32_e32 v9, v4
	v_mov_b32_e32 v4, v2
	v_pk_mul_f32 v[4:5], v[4:5], v[20:21] op_sel_hi:[1,0]
	v_mov_b32_e32 v6, v3
	v_mul_f32_e32 v2, 0xbfb8aa3b, v5
	v_exp_f32_e32 v11, v2
	v_pk_mul_f32 v[2:3], v[6:7], v[20:21] op_sel_hi:[1,0]
	v_mul_f32_e32 v1, v1, v9
	v_mul_f32_e32 v6, 0xbfb8aa3b, v3
	v_exp_f32_e32 v6, v6
	v_add_f32_e32 v7, 1.0, v11
	v_rcp_f32_e32 v7, v7
	v_mul_f32_e32 v9, v0, v1
	v_add_f32_e32 v6, 1.0, v6
	v_rcp_f32_e32 v6, v6
	v_mul_f32_e32 v0, v5, v7
	v_mul_f32_e32 v4, v4, v0
	s_mov_b64 s[4:5], -1
	v_mul_f32_e32 v0, v3, v6
	v_mul_f32_e32 v3, v2, v0
	v_cvt_pk_bf16_f32 v0, v18, v15
	v_cvt_pk_bf16_f32 v1, v16, v10
	v_cvt_pk_bf16_f32 v2, v8, v9
	v_cvt_pk_bf16_f32 v3, v4, v3
	global_store_dwordx4 v[12:13], v[0:3], off offset:2048 sc1
	s_cbranch_vccnz .LBB0_1333
	s_andn2_b64 vcc, exec, s[6:7]
	s_cbranch_vccnz .LBB0_1332
	s_barrier
	s_branch .LBB0_1332
